# attention fast loop (both copies): packed v_pk_add_f32 split into scalar adds, redundant canonicalising v_max pairs removed; on top of micro_v1
# speedup vs baseline: 1.0071x; 1.0050x over previous
; #define MFMA32(a, b, c) __builtin_amdgcn_mfma_f32_32x32x16_bf16((a), (b), (c), 0, 0, 0)
; __device__ __forceinline__ bf16x8 cat8(s16x4 lo, s16x4 hi) { return (bf16x8){lo[0], lo[1], lo[2], lo[3], hi[0], hi[1], hi[2], hi[3]}; }
; template <int KS>
; __device__ __forceinline__ void flash_fast_tile2(ldsp Ks, ldsp Vs, const FragMap<KS>& M, const bf16x8 (&qf)[KS], f32x16 (&o)[4], float& mc, float& l) {
;     ...
;         float ps0 = 0.f, ps1 = 0.f;
; #pragma unroll
;         for (int r = 0; r < 16; r += 2) { s0[r] = __builtin_amdgcn_exp2f(s0[r] - mc); s0[r + 1] = __builtin_amdgcn_exp2f(s0[r + 1] - mc); ps0 += s0[r]; ps1 += s0[r + 1]; }
;         l += ps0 + ps1;
;         const bf16x8 p0 = pack8<0>(s0), p1 = pack8<1>(s0);
; #pragma unroll
;         for (int b = 0; b < 4; ++b) {
;             o[b] = MFMA32(cat8(vl[2 * b], vh[2 * b]), p0, o[b]);
;             o[b] = MFMA32(cat8(vl[2 * b + 1], vh[2 * b + 1]), p1, o[b]); }
.LBB0_436:
	v_sub_f32_e32 v66, v66, v206
	v_sub_f32_e32 v67, v67, v206
	v_exp_f32_e32 v66, v66
	v_exp_f32_e32 v67, v67
	v_sub_f32_e32 v68, v68, v206
	v_sub_f32_e32 v69, v69, v206
	v_sub_f32_e32 v70, v70, v206
	v_sub_f32_e32 v71, v71, v206
	v_sub_f32_e32 v72, v72, v206
	v_sub_f32_e32 v73, v73, v206
	v_exp_f32_e32 v68, v68
	v_exp_f32_e32 v69, v69
	v_exp_f32_e32 v70, v70
	v_exp_f32_e32 v71, v71
	v_exp_f32_e32 v72, v72
	v_exp_f32_e32 v73, v73
	v_add_f32_e32 v212, 0, v66
	v_add_f32_e32 v213, 0, v67
	v_cvt_pk_bf16_f32 v66, v66, v67
	v_add_f32_e32 v212, v68, v212
	v_add_f32_e32 v213, v69, v213
	v_cvt_pk_bf16_f32 v67, v68, v69
	v_cvt_pk_bf16_f32 v68, v70, v71
	v_cvt_pk_bf16_f32 v69, v72, v73
	v_sub_f32_e32 v74, v74, v206
	v_sub_f32_e32 v75, v75, v206
	v_mfma_f32_32x32x16_bf16 v[50:65], v[142:145], v[66:69], v[50:65]
	v_sub_f32_e32 v76, v76, v206
	v_sub_f32_e32 v77, v77, v206
	v_sub_f32_e32 v78, v78, v206
	v_sub_f32_e32 v79, v79, v206
	v_sub_f32_e32 v80, v80, v206
	v_sub_f32_e32 v81, v81, v206
	v_exp_f32_e32 v74, v74
	s_waitcnt lgkmcnt(10)
	v_mfma_f32_32x32x16_bf16 v[34:49], v[134:137], v[66:69], v[34:49]
	v_exp_f32_e32 v75, v75
	v_exp_f32_e32 v76, v76
	v_exp_f32_e32 v77, v77
	v_exp_f32_e32 v78, v78
	v_exp_f32_e32 v79, v79
	v_exp_f32_e32 v80, v80
	v_exp_f32_e32 v81, v81
	s_waitcnt lgkmcnt(6)
	v_mfma_f32_32x32x16_bf16 v[18:33], v[126:129], v[66:69], v[18:33]
	v_add_f32_e64 v212, v70, v212
	v_add_f32_e64 v213, v71, v213
	v_cvt_pk_bf16_f32 v70, v74, v75
	v_add_f32_e64 v212, v72, v212
	v_add_f32_e64 v213, v73, v213
	v_cvt_pk_bf16_f32 v71, v76, v77
	v_cvt_pk_bf16_f32 v72, v78, v79
	v_cvt_pk_bf16_f32 v73, v80, v81
	v_add_f32_e32 v212, v74, v212
	v_add_f32_e32 v213, v75, v213
	s_waitcnt lgkmcnt(2)
	v_mfma_f32_32x32x16_bf16 v[2:17], v[114:117], v[66:69], v[2:17]
	v_add_f32_e64 v212, v76, v212
	v_add_f32_e64 v213, v77, v213
	s_movk_i32 s10, 0x2000
	v_add_f32_e64 v212, v78, v212
	v_add_f32_e64 v213, v79, v213
	s_mov_b64 s[0:1], 0
	v_add_f32_e32 v212, v80, v212
	v_add_f32_e32 v213, v81, v213
	s_andn2_b64 vcc, exec, s[4:5]
	v_add_f32_e32 v211, v212, v213
	v_mfma_f32_32x32x16_bf16 v[50:65], v[138:141], v[70:73], v[50:65]
	v_add_f32_e32 v195, v195, v211
	v_mfma_f32_32x32x16_bf16 v[34:49], v[130:133], v[70:73], v[34:49]
	v_mfma_f32_32x32x16_bf16 v[18:33], v[122:125], v[70:73], v[18:33]
	s_waitcnt lgkmcnt(0)
	v_mfma_f32_32x32x16_bf16 v[2:17], v[118:121], v[70:73], v[2:17]
	s_cbranch_vccz .LBB0_434

; __device__ __forceinline__ float xmax32(float v) { auto rr = __builtin_amdgcn_permlane32_swap(__float_as_uint(v), __float_as_uint(v), false, false); return fmaxf(__uint_as_float(rr[0]), __uint_as_float(rr[1])); }
; template <int KS>
; __device__ __forceinline__ void flash_fast_tile2(ldsp Ks, ldsp Vs, const FragMap<KS>& M, const bf16x8 (&qf)[KS], f32x16 (&o)[4], float& mc, float& l) {
;     ...
;         float m0 = fmaxf(s0[0], s0[1]), m1 = fmaxf(s0[2], s0[3]);
; #pragma unroll
;         for (int r = 4; r < 16; r += 4) { m0 = fmaxf(fmaxf(m0, s0[r]), s0[r + 1]); m1 = fmaxf(fmaxf(m1, s0[r + 2]), s0[r + 3]); }
;         const float mx = xmax32(fmaxf(m0, m1));
;         if (!__all(mx - mc <= 6.f)) {
;             const float mnew = fmaxf(mc, mx), alpha = __builtin_amdgcn_exp2f(mc - mnew);
;             mc = mnew; l *= alpha;
; #pragma unroll
;             for (int b = 0; b < 4; ++b) o[b] *= alpha;
;         }
.LBB0_439:
	s_nop 10
	v_max_f32_e32 v211, v68, v69
	v_max3_f32 v212, v66, v67, v70
	v_max3_f32 v211, v211, v72, v73
	v_max3_f32 v212, v212, v71, v74
	v_max3_f32 v211, v211, v76, v77
	v_max3_f32 v212, v212, v75, v78
	v_max3_f32 v211, v211, v80, v81
	v_max3_f32 v211, v212, v79, v211
	v_mov_b32_e32 v212, v211
	s_nop 1
	v_permlane32_swap_b32_e32 v211, v212
	v_max_f32_e32 v211, v211, v212
	v_sub_f32_e32 v212, v211, v206
	v_cmp_ge_f32_e32 vcc, s53, v212
	s_cmp_eq_u64 vcc, exec
	s_cbranch_scc1 .LBB0_436
	v_max_f32_e32 v211, v211, v211
	v_max_f32_e32 v212, v206, v206
	v_max_f32_e32 v211, v212, v211
	v_sub_f32_e32 v206, v206, v211
	v_exp_f32_e32 v206, v206
	s_nop 0
	v_mul_f32_e32 v195, v195, v206
	v_pk_mul_f32 v[64:65], v[64:65], v[206:207] op_sel_hi:[1,0]
	v_pk_mul_f32 v[62:63], v[62:63], v[206:207] op_sel_hi:[1,0]
	v_pk_mul_f32 v[60:61], v[60:61], v[206:207] op_sel_hi:[1,0]
	v_pk_mul_f32 v[58:59], v[58:59], v[206:207] op_sel_hi:[1,0]
	v_pk_mul_f32 v[56:57], v[56:57], v[206:207] op_sel_hi:[1,0]
	v_pk_mul_f32 v[54:55], v[54:55], v[206:207] op_sel_hi:[1,0]
	v_pk_mul_f32 v[52:53], v[52:53], v[206:207] op_sel_hi:[1,0]
	v_pk_mul_f32 v[50:51], v[50:51], v[206:207] op_sel_hi:[1,0]
	v_pk_mul_f32 v[48:49], v[48:49], v[206:207] op_sel_hi:[1,0]
	v_pk_mul_f32 v[46:47], v[46:47], v[206:207] op_sel_hi:[1,0]
	v_pk_mul_f32 v[44:45], v[44:45], v[206:207] op_sel_hi:[1,0]
	v_pk_mul_f32 v[42:43], v[42:43], v[206:207] op_sel_hi:[1,0]
	v_pk_mul_f32 v[40:41], v[40:41], v[206:207] op_sel_hi:[1,0]
	v_pk_mul_f32 v[38:39], v[38:39], v[206:207] op_sel_hi:[1,0]
	v_pk_mul_f32 v[36:37], v[36:37], v[206:207] op_sel_hi:[1,0]
	v_pk_mul_f32 v[34:35], v[34:35], v[206:207] op_sel_hi:[1,0]
	v_pk_mul_f32 v[32:33], v[32:33], v[206:207] op_sel_hi:[1,0]
	v_pk_mul_f32 v[30:31], v[30:31], v[206:207] op_sel_hi:[1,0]
	v_pk_mul_f32 v[28:29], v[28:29], v[206:207] op_sel_hi:[1,0]
	v_pk_mul_f32 v[26:27], v[26:27], v[206:207] op_sel_hi:[1,0]
	v_pk_mul_f32 v[24:25], v[24:25], v[206:207] op_sel_hi:[1,0]
	v_pk_mul_f32 v[22:23], v[22:23], v[206:207] op_sel_hi:[1,0]
	v_pk_mul_f32 v[20:21], v[20:21], v[206:207] op_sel_hi:[1,0]
	v_pk_mul_f32 v[18:19], v[18:19], v[206:207] op_sel_hi:[1,0]
	v_pk_mul_f32 v[16:17], v[16:17], v[206:207] op_sel_hi:[1,0]
	v_pk_mul_f32 v[14:15], v[14:15], v[206:207] op_sel_hi:[1,0]
	v_pk_mul_f32 v[12:13], v[12:13], v[206:207] op_sel_hi:[1,0]
	v_pk_mul_f32 v[10:11], v[10:11], v[206:207] op_sel_hi:[1,0]
	v_pk_mul_f32 v[8:9], v[8:9], v[206:207] op_sel_hi:[1,0]
	v_pk_mul_f32 v[6:7], v[6:7], v[206:207] op_sel_hi:[1,0]
	v_pk_mul_f32 v[4:5], v[4:5], v[206:207] op_sel_hi:[1,0]
	v_pk_mul_f32 v[2:3], v[2:3], v[206:207] op_sel_hi:[1,0]
	v_mov_b32_e32 v206, v211
	s_branch .LBB0_436

; #define MFMA32(a, b, c) __builtin_amdgcn_mfma_f32_32x32x16_bf16((a), (b), (c), 0, 0, 0)
; __device__ __forceinline__ bf16x8 cat8(s16x4 lo, s16x4 hi) { return (bf16x8){lo[0], lo[1], lo[2], lo[3], hi[0], hi[1], hi[2], hi[3]}; }
; template <int KS>
; __device__ __forceinline__ void flash_fast_tile2(ldsp Ks, ldsp Vs, const FragMap<KS>& M, const bf16x8 (&qf)[KS], f32x16 (&o)[4], float& mc, float& l) {
;     ...
;         float ps0 = 0.f, ps1 = 0.f;
; #pragma unroll
;         for (int r = 0; r < 16; r += 2) { s0[r] = __builtin_amdgcn_exp2f(s0[r] - mc); s0[r + 1] = __builtin_amdgcn_exp2f(s0[r + 1] - mc); ps0 += s0[r]; ps1 += s0[r + 1]; }
;         l += ps0 + ps1;
;         const bf16x8 p0 = pack8<0>(s0), p1 = pack8<1>(s0);
; #pragma unroll
;         for (int b = 0; b < 4; ++b) {
;             o[b] = MFMA32(cat8(vl[2 * b], vh[2 * b]), p0, o[b]);
;             o[b] = MFMA32(cat8(vl[2 * b + 1], vh[2 * b + 1]), p1, o[b]); }
.LBB0_460:
	v_sub_f32_e32 v80, v80, v207
	v_sub_f32_e32 v81, v81, v207
	v_exp_f32_e32 v80, v80
	v_exp_f32_e32 v81, v81
	v_sub_f32_e32 v82, v82, v207
	v_sub_f32_e32 v83, v83, v207
	v_sub_f32_e32 v84, v84, v207
	v_sub_f32_e32 v85, v85, v207
	v_sub_f32_e32 v86, v86, v207
	v_sub_f32_e32 v87, v87, v207
	v_exp_f32_e32 v82, v82
	v_exp_f32_e32 v83, v83
	v_exp_f32_e32 v84, v84
	v_exp_f32_e32 v85, v85
	v_exp_f32_e32 v86, v86
	v_exp_f32_e32 v87, v87
	v_add_f32_e32 v252, 0, v80
	v_add_f32_e32 v253, 0, v81
	v_cvt_pk_bf16_f32 v80, v80, v81
	v_add_f32_e32 v252, v82, v252
	v_add_f32_e32 v253, v83, v253
	v_cvt_pk_bf16_f32 v81, v82, v83
	v_cvt_pk_bf16_f32 v82, v84, v85
	v_cvt_pk_bf16_f32 v83, v86, v87
	v_sub_f32_e32 v88, v88, v207
	v_sub_f32_e32 v89, v89, v207
	v_mfma_f32_32x32x16_bf16 v[64:79], v[144:147], v[80:83], v[64:79]
	v_sub_f32_e32 v90, v90, v207
	v_sub_f32_e32 v91, v91, v207
	v_sub_f32_e32 v92, v92, v207
	v_sub_f32_e32 v93, v93, v207
	v_sub_f32_e32 v94, v94, v207
	v_sub_f32_e32 v95, v95, v207
	v_exp_f32_e32 v88, v88
	s_waitcnt lgkmcnt(10)
	v_mfma_f32_32x32x16_bf16 v[48:63], v[136:139], v[80:83], v[48:63]
	v_exp_f32_e32 v89, v89
	v_exp_f32_e32 v90, v90
	v_exp_f32_e32 v91, v91
	v_exp_f32_e32 v92, v92
	v_exp_f32_e32 v93, v93
	v_exp_f32_e32 v94, v94
	v_exp_f32_e32 v95, v95
	s_waitcnt lgkmcnt(6)
	v_mfma_f32_32x32x16_bf16 v[32:47], v[128:131], v[80:83], v[32:47]
	v_add_f32_e64 v252, v84, v252
	v_add_f32_e64 v253, v85, v253
	v_cvt_pk_bf16_f32 v84, v88, v89
	v_add_f32_e64 v252, v86, v252
	v_add_f32_e64 v253, v87, v253
	v_cvt_pk_bf16_f32 v85, v90, v91
	v_cvt_pk_bf16_f32 v86, v92, v93
	v_cvt_pk_bf16_f32 v87, v94, v95
	v_add_f32_e32 v252, v88, v252
	v_add_f32_e32 v253, v89, v253
	s_waitcnt lgkmcnt(2)
	v_mfma_f32_32x32x16_bf16 v[16:31], v[116:119], v[80:83], v[16:31]
	v_add_f32_e64 v252, v90, v252
	v_add_f32_e64 v253, v91, v253
	s_movk_i32 s28, 0x2000
	v_add_f32_e64 v252, v92, v252
	v_add_f32_e64 v253, v93, v253
	s_mov_b64 s[0:1], 0
	v_add_f32_e32 v252, v94, v252
	v_add_f32_e32 v253, v95, v253
	s_andn2_b64 vcc, exec, s[4:5]
	v_add_f32_e32 v211, v252, v253
	v_mfma_f32_32x32x16_bf16 v[64:79], v[140:143], v[84:87], v[64:79]
	v_add_f32_e32 v195, v195, v211
	v_mfma_f32_32x32x16_bf16 v[48:63], v[132:135], v[84:87], v[48:63]
	v_mfma_f32_32x32x16_bf16 v[32:47], v[124:127], v[84:87], v[32:47]
	s_waitcnt lgkmcnt(0)
	v_mfma_f32_32x32x16_bf16 v[16:31], v[120:123], v[84:87], v[16:31]
	s_cbranch_vccz .LBB0_458

; __device__ __forceinline__ float xmax32(float v) { auto rr = __builtin_amdgcn_permlane32_swap(__float_as_uint(v), __float_as_uint(v), false, false); return fmaxf(__uint_as_float(rr[0]), __uint_as_float(rr[1])); }
; template <int KS>
; __device__ __forceinline__ void flash_fast_tile2(ldsp Ks, ldsp Vs, const FragMap<KS>& M, const bf16x8 (&qf)[KS], f32x16 (&o)[4], float& mc, float& l) {
;     ...
;         float m0 = fmaxf(s0[0], s0[1]), m1 = fmaxf(s0[2], s0[3]);
; #pragma unroll
;         for (int r = 4; r < 16; r += 4) { m0 = fmaxf(fmaxf(m0, s0[r]), s0[r + 1]); m1 = fmaxf(fmaxf(m1, s0[r + 2]), s0[r + 3]); }
;         const float mx = xmax32(fmaxf(m0, m1));
;         if (!__all(mx - mc <= 6.f)) {
;             const float mnew = fmaxf(mc, mx), alpha = __builtin_amdgcn_exp2f(mc - mnew);
;             mc = mnew; l *= alpha;
; #pragma unroll
;             for (int b = 0; b < 4; ++b) o[b] *= alpha;
;         }
.LBB0_463:
	s_nop 10
	v_max_f32_e32 v211, v82, v83
	v_max3_f32 v213, v80, v81, v84
	v_max3_f32 v211, v211, v86, v87
	v_max3_f32 v213, v213, v85, v88
	v_max3_f32 v211, v211, v90, v91
	v_max3_f32 v213, v213, v89, v92
	v_max3_f32 v211, v211, v94, v95
	v_max3_f32 v211, v213, v93, v211
	v_mov_b32_e32 v213, v211
	s_nop 1
	v_permlane32_swap_b32_e32 v211, v213
	v_max_f32_e32 v211, v211, v213
	v_sub_f32_e32 v213, v211, v207
	v_cmp_ge_f32_e32 vcc, s53, v213
	s_cmp_eq_u64 vcc, exec
	s_cbranch_scc1 .LBB0_460
	v_max_f32_e32 v211, v211, v211
	v_max_f32_e32 v213, v207, v207
	v_max_f32_e32 v211, v213, v211
	v_sub_f32_e32 v207, v207, v211
	v_exp_f32_e32 v252, v207
	v_mov_b32_e32 v207, v211
	v_mul_f32_e32 v195, v195, v252
	v_pk_mul_f32 v[78:79], v[78:79], v[252:253] op_sel_hi:[1,0]
	v_pk_mul_f32 v[76:77], v[76:77], v[252:253] op_sel_hi:[1,0]
	v_pk_mul_f32 v[74:75], v[74:75], v[252:253] op_sel_hi:[1,0]
	v_pk_mul_f32 v[72:73], v[72:73], v[252:253] op_sel_hi:[1,0]
	v_pk_mul_f32 v[70:71], v[70:71], v[252:253] op_sel_hi:[1,0]
	v_pk_mul_f32 v[68:69], v[68:69], v[252:253] op_sel_hi:[1,0]
	v_pk_mul_f32 v[66:67], v[66:67], v[252:253] op_sel_hi:[1,0]
	v_pk_mul_f32 v[64:65], v[64:65], v[252:253] op_sel_hi:[1,0]
	v_pk_mul_f32 v[62:63], v[62:63], v[252:253] op_sel_hi:[1,0]
	v_pk_mul_f32 v[60:61], v[60:61], v[252:253] op_sel_hi:[1,0]
	v_pk_mul_f32 v[58:59], v[58:59], v[252:253] op_sel_hi:[1,0]
	v_pk_mul_f32 v[56:57], v[56:57], v[252:253] op_sel_hi:[1,0]
	v_pk_mul_f32 v[54:55], v[54:55], v[252:253] op_sel_hi:[1,0]
	v_pk_mul_f32 v[52:53], v[52:53], v[252:253] op_sel_hi:[1,0]
	v_pk_mul_f32 v[50:51], v[50:51], v[252:253] op_sel_hi:[1,0]
	v_pk_mul_f32 v[48:49], v[48:49], v[252:253] op_sel_hi:[1,0]
	v_pk_mul_f32 v[46:47], v[46:47], v[252:253] op_sel_hi:[1,0]
	v_pk_mul_f32 v[44:45], v[44:45], v[252:253] op_sel_hi:[1,0]
	v_pk_mul_f32 v[42:43], v[42:43], v[252:253] op_sel_hi:[1,0]
	v_pk_mul_f32 v[40:41], v[40:41], v[252:253] op_sel_hi:[1,0]
	v_pk_mul_f32 v[38:39], v[38:39], v[252:253] op_sel_hi:[1,0]
	v_pk_mul_f32 v[36:37], v[36:37], v[252:253] op_sel_hi:[1,0]
	v_pk_mul_f32 v[34:35], v[34:35], v[252:253] op_sel_hi:[1,0]
	v_pk_mul_f32 v[32:33], v[32:33], v[252:253] op_sel_hi:[1,0]
	v_pk_mul_f32 v[30:31], v[30:31], v[252:253] op_sel_hi:[1,0]
	v_pk_mul_f32 v[28:29], v[28:29], v[252:253] op_sel_hi:[1,0]
	v_pk_mul_f32 v[26:27], v[26:27], v[252:253] op_sel_hi:[1,0]
	v_pk_mul_f32 v[24:25], v[24:25], v[252:253] op_sel_hi:[1,0]
	v_pk_mul_f32 v[22:23], v[22:23], v[252:253] op_sel_hi:[1,0]
	v_pk_mul_f32 v[20:21], v[20:21], v[252:253] op_sel_hi:[1,0]
	v_pk_mul_f32 v[18:19], v[18:19], v[252:253] op_sel_hi:[1,0]
	v_pk_mul_f32 v[16:17], v[16:17], v[252:253] op_sel_hi:[1,0]
	s_branch .LBB0_460
